# attention V tile LDS layout: one ds_read_b128 per PV operand, 24 v_mov per tile removed, staging write as two ds_write_b64
# speedup vs baseline: 1.0127x; 1.0029x over previous
; DEVI void attn_item(const P& p, int item, char* smem) {
;     const int tid = threadIdx.x, lane = tid & 63, w = tid >> 6, fr = lane & 15, fq = lane >> 4;
;     const int qt = item & 63, kvh = (item >> 6) & 3, b = item >> 8;
;     const int head = kvh * 4 + w, q0 = qt * 64;
;     const bf16_t* Q = (const bf16_t*)(p.ws + OFF_B) + ((size_t)(b * SEQ + q0)) * 1024 + head * 64;
;     const bf16_t* KB = (const bf16_t*)(p.ws + OFF_D);
;     const bf16_t* VT = (const bf16_t*)(p.ws + OFF_D + 17 * MiB);
;     char* sK = smem;
;     char* sV = smem + 8192;
;     const float sinkv = p.sink[head] * LOG2E;
;     const bf16_t* SGT = (const bf16_t*)(p.ws + OFF_C) + ((size_t)(b * SEQ + q0)) * 1024 + head * 64;
;     bf16_t* OG = (bf16_t*)(p.ws + OFF_A) + ((size_t)(b * SEQ + q0)) * 1024 + head * 64;
;     ...
;                     const int row = 16 * nd + fr, x2 = 2 * ((row >> 1) & 7);
;                     const uint2 lo = *(const uint2*)(sV + row * 128 + (((8 * kk + fq) ^ x2) << 3));
;                     const uint2 hi = *(const uint2*)(sV + row * 128 + (((8 * kk + 4 + fq) ^ x2) << 3));
.LBB0_1427:
	s_or_b64 exec, exec, s[2:3]
	s_cmpk_gt_i32 s86, 0x7ff
	s_barrier
	s_cbranch_scc1 .LBB0_1444
	v_xor_b32_e32 v4, v216, v172
	v_lshlrev_b32_e32 v4, 4, v4
	v_and_b32_e32 v4, 0x70, v4
	v_bfe_u32 v3, v172, 4, 2
	v_add_u32_e32 v123, 0, v4
	v_and_b32_e32 v4, 7, v172
	v_mov_b32_e32 v1, 0
	s_movk_i32 s2, 0x70
	v_and_b32_e32 v0, 0x70, v182
	v_and_b32_e32 v6, 14, v172
	v_bitop3_b32 v7, v175, v4, 3 bitop3:0x6c
	v_bitop3_b32 v4, v3, v4, 4 bitop3:0x36
	v_lshl_add_u64 v[98:99], s[54:55], 0, v[0:1]
	v_lshl_add_u64 v[100:101], s[0:1], 0, v[0:1]
	v_bitop3_b32 v0, v182, s2, v172 bitop3:0x48
	v_lshlrev_b32_e32 v125, 2, v3
	v_lshlrev_b32_e32 v8, 4, v4
	v_bitop3_b32 v4, v175, v6, 3 bitop3:0x6c
	v_add_u32_e32 v124, 0, v0
	v_sub_u32_e32 v0, v174, v125
	v_lshlrev_b32_e32 v9, 3, v4
	v_bitop3_b32 v4, v3, v6, 4 bitop3:0x36
	v_lshlrev_b32_e32 v2, 3, v3
	v_cmp_eq_u32_e32 vcc, 0, v3
	v_add_u32_e32 v126, 0x7f, v0
	v_lshrrev_b32_e32 v0, 2, v172
	v_lshlrev_b32_e32 v10, 3, v4
	v_bitop3_b32 v4, v3, v6, 8 bitop3:0x36
	v_bitop3_b32 v3, v3, v6, 12 bitop3:0x36
	v_lshl_add_u32 v5, v174, 7, 0
	v_and_b32_e32 v0, 8, v0
	v_add_u32_e32 v128, 32, v216
	v_lshlrev_b32_e32 v7, 4, v7
	v_lshlrev_b32_e32 v11, 3, v4
	v_lshlrev_b32_e32 v3, 3, v3
	v_and_b32_e32 v4, 16, v172
	s_mov_b32 s29, 0
	v_cndmask_b32_e64 v121, 0, 1.0, vcc
	v_lshlrev_b32_e32 v127, 7, v216
	v_lshlrev_b32_e32 v129, 7, v128
	s_lshl_b32 s34, s86, 6
	s_lshl_b32 s35, s27, 6
	v_lshlrev_b32_e32 v102, 1, v2
	v_mov_b32_e32 v103, v1
	v_lshlrev_b32_e32 v104, 1, v0
	v_mov_b32_e32 v105, v1
	s_movk_i32 s36, 0x2200
	v_lshlrev_b32_e32 v106, 1, v4
	v_mov_b32_e32 v107, v1
	v_add_u32_e32 v130, v5, v7
	v_add_u32_e32 v131, v5, v8
	s_movk_i32 s37, 0xfeff
	s_movk_i32 s38, 0x101
	s_movk_i32 s39, 0xfefe
	v_add_u32_e32 v132, v5, v9
	v_add_u32_e32 v133, v5, v10
	v_add_u32_e32 v134, v5, v11
	v_add_u32_e32 v135, v5, v3
	v_and_b32_e32 v2, 7, v172
	v_and_b32_e32 v3, 4, v2
	v_and_b32_e32 v4, 1, v2
	v_lshl_or_b32 v3, v4, 1, v3
	v_bfe_u32 v4, v216, 1, 3
	v_xor_b32_e32 v3, v3, v4
	v_bfe_u32 v4, v2, 1, 1
	v_lshlrev_b32_e32 v4, 3, v4
	v_lshl_or_b32 v124, v3, 4, v4
	v_xor_b32_e32 v228, 16, v124
	v_bfe_u32 v2, v172, 4, 2
	v_bfe_u32 v3, v174, 1, 3
	v_xor_b32_e32 v2, v2, v3
	v_lshl_add_u32 v132, v2, 4, v5
	v_xor_b32_e32 v134, 64, v132
	v_mov_b32_e32 v136, 0xf149f2ca
	s_mov_b32 s42, s86
	s_branch .LBB0_1430

; DEVI unsigned pk2(float lo, float hi) { f32x2 v = {lo, hi}; bf16x2_t b = __builtin_convertvector(v, bf16x2_t); return __builtin_bit_cast(unsigned, b); }
; DEVI void attn_item(const P& p, int item, char* smem) {
;     ...
;                 float mx = s[0][0];
; #pragma unroll
;                 for (int n = 0; n < 4; ++n)
; #pragma unroll
;                     for (int j = 0; j < 4; ++j) mx = fmaxf(mx, s[n][j]);
;                 mx = rowmax4(mx);
;                 const float mnew = fmaxf(mrow[m], mx);
;                 const float alpha = __builtin_amdgcn_exp2f(mrow[m] - mnew);
;                 mrow[m] = mnew;
;                 float ls = 0.f;
; #pragma unroll
;                 for (int n = 0; n < 4; ++n)
; #pragma unroll
;                     for (int j = 0; j < 4; ++j) { s[n][j] = __builtin_amdgcn_exp2f(s[n][j] - mnew); ls += s[n][j]; }
;                 lrow[m] = lrow[m] * alpha + ls;
; #pragma unroll
;                 for (int nd = 0; nd < 4; ++nd) O[nd][m] *= alpha;
; #pragma unroll
;                 for (int kk = 0; kk < 2; ++kk) {
;                     union { uint4 u; bf16x8 v; } cv;
;                     cv.u.x = pk2(s[2 * kk][0], s[2 * kk][1]); cv.u.y = pk2(s[2 * kk][2], s[2 * kk][3]);
;                     cv.u.z = pk2(s[2 * kk + 1][0], s[2 * kk + 1][1]); cv.u.w = pk2(s[2 * kk + 1][2], s[2 * kk + 1][3]);
;                     Pf[m][kk] = cv.v;
;                 }
;             }
; #pragma unroll
;             for (int nd = 0; nd < 4; ++nd)
; #pragma unroll
;                 for (int kk = 0; kk < 2; ++kk) {
;                     const int row = 16 * nd + fr, x2 = 2 * ((row >> 1) & 7);
;                     const uint2 lo = *(const uint2*)(sV + row * 128 + (((8 * kk + fq) ^ x2) << 3));
;                     const uint2 hi = *(const uint2*)(sV + row * 128 + (((8 * kk + 4 + fq) ^ x2) << 3));
;                     union { uint4 u; bf16x8 v; } cv;
;                     cv.u.x = lo.x; cv.u.y = lo.y; cv.u.z = hi.x; cv.u.w = hi.y;
; #pragma unroll
;                     for (int m = 0; m < 2; ++m) O[nd][m] = __builtin_amdgcn_mfma_f32_16x16x32_bf16(cv.v, Pf[m][kk], O[nd][m], 0, 0, 0);
;                 }
.LBB0_1433:
	v_max3_f32 v91, v160, v86, v87
	v_sub_f32_e32 v0, v78, v91
	v_exp_f32_e32 v78, v0
	v_sub_f32_e32 v79, v79, v91
	v_exp_f32_e32 v79, v79
	v_sub_f32_e32 v80, v80, v91
	v_exp_f32_e32 v80, v80
	v_sub_f32_e32 v81, v81, v91
	v_exp_f32_e32 v81, v81
	v_sub_f32_e32 v74, v74, v91
	v_add_f32_e32 v82, 0, v78
	v_exp_f32_e32 v74, v74
	v_sub_f32_e32 v75, v75, v91
	v_add_f32_e32 v82, v79, v82
	v_exp_f32_e32 v75, v75
	v_sub_f32_e32 v76, v76, v91
	v_add_f32_e32 v82, v80, v82
	v_exp_f32_e32 v76, v76
	v_sub_f32_e32 v77, v77, v91
	v_add_f32_e32 v82, v81, v82
	v_exp_f32_e32 v77, v77
	v_sub_f32_e32 v58, v58, v91
	v_add_f32_e32 v82, v74, v82
	v_exp_f32_e32 v58, v58
	v_sub_f32_e32 v59, v59, v91
	v_add_f32_e32 v82, v75, v82
	v_exp_f32_e32 v59, v59
	v_add_f32_e32 v82, v76, v82
	v_add_f32_e32 v82, v77, v82
	v_add_f32_e32 v82, v58, v82
	v_sub_f32_e32 v50, v50, v91
	v_sub_f32_e32 v51, v51, v91
	v_exp_f32_e32 v83, v50
	v_add_f32_e32 v50, v59, v82
	v_exp_f32_e32 v82, v51
	v_sub_f32_e32 v51, v52, v91
	v_cvt_pk_bf16_f32 v52, v74, v75
	v_max_f32_e32 v74, v70, v71
	v_max3_f32 v74, v74, v72, v73
	v_max3_f32 v74, v74, v62, v63
	v_max3_f32 v74, v74, v64, v65
	v_max3_f32 v74, v74, v54, v55
	v_sub_f32_e32 v60, v60, v91
	v_max3_f32 v74, v74, v56, v57
	v_exp_f32_e32 v60, v60
	v_sub_f32_e32 v61, v61, v91
	v_max3_f32 v74, v74, v66, v67
	v_exp_f32_e32 v61, v61
	v_max3_f32 v74, v74, v68, v69
	v_mov_b32_e32 v75, v74
	s_nop 1
	v_permlane32_swap_b32_e32 v74, v75
	v_add_f32_e32 v50, v60, v50
	v_exp_f32_e32 v84, v51
	v_sub_f32_e32 v51, v53, v91
	v_sub_f32_e32 v0, v160, v91
	v_add_f32_e32 v50, v61, v50
	v_exp_f32_e32 v85, v51
	v_max_f32_e32 v74, v74, v75
	v_add_f32_e32 v50, v83, v50
	v_exp_f32_e32 v0, v0
	v_mov_b32_e32 v75, v74
	v_add_f32_e32 v50, v82, v50
	s_nop 0
	v_permlane16_swap_b32_e32 v74, v75
	v_add_f32_e32 v50, v84, v50
	v_max3_f32 v93, v159, v74, v75
	v_add_f32_e32 v92, v85, v50
	v_sub_f32_e32 v54, v54, v93
	v_fmac_f32_e32 v92, v158, v0
	v_exp_f32_e32 v158, v54
	v_sub_f32_e32 v54, v55, v93
	v_sub_f32_e32 v74, v159, v93
	v_exp_f32_e32 v159, v54
	v_sub_f32_e32 v54, v56, v93
	v_exp_f32_e32 v160, v54
	v_sub_f32_e32 v54, v57, v93
	v_sub_f32_e32 v62, v62, v93
	v_exp_f32_e32 v161, v54
	v_sub_f32_e32 v54, v66, v93
	v_exp_f32_e32 v94, v62
	v_sub_f32_e32 v62, v63, v93
	v_exp_f32_e32 v162, v54
	v_sub_f32_e32 v54, v67, v93
	v_exp_f32_e32 v95, v62
	v_sub_f32_e32 v62, v64, v93
	v_exp_f32_e32 v163, v54
	v_sub_f32_e32 v54, v68, v93
	v_exp_f32_e32 v96, v62
	v_sub_f32_e32 v62, v65, v93
	v_exp_f32_e32 v164, v54
	v_sub_f32_e32 v54, v69, v93
	v_exp_f32_e32 v97, v62
	v_exp_f32_e32 v165, v54
	ds_read_b128 v[54:57], v132 offset:8192
	ds_read_b128 v[62:65], v132 offset:10240
	v_sub_f32_e32 v70, v70, v93
	v_exp_f32_e32 v86, v70
	v_sub_f32_e32 v70, v71, v93
	v_exp_f32_e32 v87, v70
	v_sub_f32_e32 v70, v72, v93
	v_cvt_pk_bf16_f32 v50, v78, v79
	v_cvt_pk_bf16_f32 v51, v80, v81
	v_cvt_pk_bf16_f32 v53, v76, v77
	v_exp_f32_e32 v88, v70
	v_sub_f32_e32 v70, v73, v93
	v_exp_f32_e32 v90, v74
	ds_read_b128 v[74:77], v134 offset:8192
	ds_read_b128 v[78:81], v134 offset:10240
	v_exp_f32_e32 v89, v70
	s_waitcnt lgkmcnt(3)
	s_waitcnt lgkmcnt(2)
	v_pk_mul_f32 v[40:41], v[40:41], v[0:1] op_sel_hi:[1,0]
	v_pk_mul_f32 v[38:39], v[38:39], v[0:1] op_sel_hi:[1,0]
	v_pk_mul_f32 v[44:45], v[44:45], v[0:1] op_sel_hi:[1,0]
	v_pk_mul_f32 v[42:43], v[42:43], v[0:1] op_sel_hi:[1,0]
	v_cvt_pk_bf16_f32 v58, v58, v59
	v_cvt_pk_bf16_f32 v59, v60, v61
	v_cvt_pk_bf16_f32 v60, v83, v82
	v_cvt_pk_bf16_f32 v61, v84, v85
	v_pk_mul_f32 v[16:17], v[16:17], v[90:91] op_sel_hi:[1,0]
	v_pk_mul_f32 v[14:15], v[14:15], v[90:91] op_sel_hi:[1,0]
	v_cvt_pk_bf16_f32 v66, v86, v87
	v_cvt_pk_bf16_f32 v67, v88, v89
	v_cvt_pk_bf16_f32 v68, v94, v95
	v_cvt_pk_bf16_f32 v69, v96, v97
	s_waitcnt lgkmcnt(1)
	s_waitcnt lgkmcnt(0)
	v_pk_mul_f32 v[12:13], v[12:13], v[90:91] op_sel_hi:[1,0]
	v_pk_mul_f32 v[10:11], v[10:11], v[90:91] op_sel_hi:[1,0]
	v_pk_mul_f32 v[48:49], v[48:49], v[0:1] op_sel_hi:[1,0]
	v_pk_mul_f32 v[46:47], v[46:47], v[0:1] op_sel_hi:[1,0]
	v_mfma_f32_16x16x32_bf16 v[38:41], v[54:57], v[50:53], v[38:41]
	v_mul_f32_e64 v20, v20, v0
	v_mul_f32_e64 v21, v21, v0
	v_pk_mul_f32 v[18:19], v[18:19], v[0:1] op_sel_hi:[1,0]
	v_add_f32_e32 v0, 0, v86
	v_mfma_f32_16x16x32_bf16 v[14:17], v[54:57], v[66:69], v[14:17]
	ds_read_b128 v[54:57], v132 offset:12288
	v_add_f32_e32 v0, v87, v0
	v_add_f32_e32 v0, v88, v0
	v_mfma_f32_16x16x32_bf16 v[42:45], v[62:65], v[50:53], v[42:45]
	v_cvt_pk_bf16_f32 v70, v158, v159
	v_cvt_pk_bf16_f32 v71, v160, v161
	v_cvt_pk_bf16_f32 v72, v162, v163
	v_mfma_f32_16x16x32_bf16 v[10:13], v[62:65], v[66:69], v[10:13]
	ds_read_b128 v[62:65], v132 offset:14336
	v_cvt_pk_bf16_f32 v73, v164, v165
	v_add_f32_e32 v0, v89, v0
	v_mfma_f32_16x16x32_bf16 v[38:41], v[74:77], v[58:61], v[38:41]
	v_add_f32_e32 v0, v94, v0
	s_waitcnt lgkmcnt(1)
	v_mfma_f32_16x16x32_bf16 v[14:17], v[74:77], v[70:73], v[14:17]
	ds_read_b128 v[74:77], v134 offset:12288
	s_waitcnt lgkmcnt(1)
	v_mfma_f32_16x16x32_bf16 v[42:45], v[78:81], v[58:61], v[42:45]
	v_add_f32_e32 v0, v95, v0
	v_mfma_f32_16x16x32_bf16 v[10:13], v[78:81], v[70:73], v[10:13]
	ds_read_b128 v[78:81], v134 offset:14336
	v_add_f32_e32 v0, v96, v0
	v_add_f32_e32 v0, v97, v0
	v_add_f32_e32 v0, v158, v0
	v_pk_mul_f32 v[8:9], v[8:9], v[90:91] op_sel_hi:[1,0]
	v_pk_mul_f32 v[6:7], v[6:7], v[90:91] op_sel_hi:[1,0]
	s_waitcnt lgkmcnt(0)
	v_add_f32_e32 v0, v159, v0
	v_pk_mul_f32 v[4:5], v[4:5], v[90:91] op_sel_hi:[1,0]
	v_pk_mul_f32 v[2:3], v[2:3], v[90:91] op_sel_hi:[1,0]
	v_mfma_f32_16x16x32_bf16 v[46:49], v[54:57], v[50:53], v[46:49]
	v_add_f32_e32 v0, v160, v0
	v_add_f32_e32 v0, v161, v0
	v_add_f32_e32 v0, v162, v0
	v_mfma_f32_16x16x32_bf16 v[6:9], v[54:57], v[66:69], v[6:9]
	v_add_f32_e32 v0, v163, v0
	v_add_f32_e32 v0, v164, v0
	v_add_f32_e32 v0, v165, v0
	v_mfma_f32_16x16x32_bf16 v[18:21], v[62:65], v[50:53], v[18:21]
	v_fmac_f32_e32 v0, v139, v90
	v_mov_b32_e32 v159, v93
	v_mov_b32_e32 v160, v91
	v_mfma_f32_16x16x32_bf16 v[2:5], v[62:65], v[66:69], v[2:5]
	v_mov_b32_e32 v139, v0
	v_mov_b32_e32 v158, v92
	v_mfma_f32_16x16x32_bf16 v[46:49], v[74:77], v[58:61], v[46:49]
	v_mfma_f32_16x16x32_bf16 v[6:9], v[74:77], v[70:73], v[6:9]
	v_mfma_f32_16x16x32_bf16 v[18:21], v[78:81], v[58:61], v[18:21]
	v_mfma_f32_16x16x32_bf16 v[2:5], v[78:81], v[70:73], v[2:5]

; DEVI void attn_item(const P& p, int item, char* smem) {
;     ...
;             __syncthreads();
; #pragma unroll
;             for (int i = 0; i < 2; ++i) {
;                 const int row = (tid >> 3) + 32 * i, ch = tid & 7;
;                 const uint4 kv = *(const uint4*)(KB + ((size_t)(b * TPB + tok0 + row)) * 256 + kvh * 64 + ch * 8);
;                 *(uint4*)(sK + row * 128 + ((ch ^ (row & 7)) << 4)) = kv;
;                 const uint4 vv = *(const uint4*)(VT + ((size_t)(b * 256 + kvh * 64 + row)) * TPB + tok0 + ch * 8);
;                 *(uint4*)(sV + row * 128 + ((ch ^ ((row >> 1) & 7)) << 4)) = vv;
;             }
;             __syncthreads();
.Lat_have:
	s_barrier
	v_add_u32_e32 v66, v123, v127
	v_add_u32_e32 v67, v124, v127
	v_add_u32_e32 v68, v123, v129
	v_add_u32_e32 v69, v124, v129
	v_add_u32_e32 v50, v228, v127
	v_add_u32_e32 v51, v228, v129
	s_and_b32 s4, s28, 11
	s_cmp_eq_u32 s4, 0
	s_cselect_b64 s[18:19], -1, 0
	s_and_b64 s[18:19], s[2:3], s[18:19]
	s_andn2_b64 vcc, exec, s[18:19]
	s_cbranch_vccnz .Lat_noprep
	v_sub_u32_e32 v0, s30, v140
	v_subrev_u32_e32 v171, s30, v142
	v_subrev_u32_e32 v170, s30, v143
	v_subrev_u32_e32 v168, s30, v144
	v_subrev_u32_e32 v169, s30, v145
	v_subrev_u32_e32 v165, s30, v146
	v_subrev_u32_e32 v162, s30, v147
	v_subrev_u32_e32 v166, s30, v148
	v_subrev_u32_e32 v163, s30, v149
	v_subrev_u32_e32 v167, s30, v150
	v_subrev_u32_e32 v164, s30, v151
	v_subrev_u32_e32 v161, s30, v140
	v_cmp_gt_u32_e64 s[4:5], s38, v0
	v_cmp_lt_u32_e64 s[6:7], s39, v171
	v_cmp_lt_u32_e64 s[8:9], s39, v170
	v_cmp_lt_u32_e64 s[10:11], s39, v168
	v_cmp_lt_u32_e64 s[12:13], s39, v169
	v_cmp_lt_u32_e64 s[14:15], s39, v165
	v_cmp_lt_u32_e64 s[16:17], s39, v162
	v_cmp_lt_u32_e64 s[20:21], s39, v163
	v_cmp_lt_u32_e64 s[22:23], s39, v167
	v_cmp_lt_u32_e64 s[24:25], s39, v164
.Lat_noprep:
	s_waitcnt vmcnt(0)
	ds_write_b128 v66, v[190:193]
	ds_write_b64 v67, v[194:195] offset:8192
	ds_write_b64 v50, v[196:197] offset:8192
	ds_write_b128 v68, v[198:201]
	ds_write_b64 v69, v[202:203] offset:8192
	ds_write_b64 v51, v[204:205] offset:8192
	s_mov_b32 s99, 0
	s_cmp_lt_u32 s28, 8
	s_cbranch_scc0 .Lat_nopf
	s_cmp_gt_u32 s28, 3
	s_cbranch_scc1 .Lat_ctx
	s_add_i32 s100, s47, 64
	s_add_i32 s98, s100, 0xffffff00
	s_cmpk_lt_u32 s98, 0x1000
	s_cbranch_scc0 .Lat_nopf
	s_branch .Lat_issue
